# removed the unused cooperative grid.sync at kernel entry (nothing depends on it; the XCD barrier self-synchronizes on first use)
# speedup vs baseline: 1.0007x; 1.0007x over previous
.LBB0_15:
	s_load_dwordx16 s[48:63], s[0:1], 0x0
	s_cmp_ge_i32 s40, s41
	s_barrier
	s_waitcnt lgkmcnt(0)
	v_writelane_b32 v250, s48, 10
	s_nop 1
	v_writelane_b32 v250, s49, 11
	v_writelane_b32 v250, s50, 12
	v_writelane_b32 v250, s51, 13
	v_writelane_b32 v250, s52, 14
	v_writelane_b32 v250, s53, 15
	v_writelane_b32 v250, s54, 16
	v_writelane_b32 v250, s55, 17
	v_writelane_b32 v250, s56, 18
	v_writelane_b32 v250, s57, 19
	v_writelane_b32 v250, s58, 20
	v_writelane_b32 v250, s59, 21
	v_writelane_b32 v250, s60, 22
	v_writelane_b32 v250, s61, 23
	v_writelane_b32 v250, s62, 24
	v_writelane_b32 v250, s63, 25
	s_load_dwordx16 s[48:63], s[0:1], 0x40
	s_waitcnt lgkmcnt(0)
	v_writelane_b32 v250, s48, 26
	s_nop 1
	v_writelane_b32 v250, s49, 27
	v_writelane_b32 v250, s50, 28
	v_writelane_b32 v250, s51, 29
	v_writelane_b32 v250, s52, 30
	v_writelane_b32 v250, s53, 31
	v_writelane_b32 v250, s54, 32
	v_writelane_b32 v250, s55, 33
	v_writelane_b32 v250, s56, 34
	v_writelane_b32 v250, s57, 35
	v_writelane_b32 v250, s58, 36
	v_writelane_b32 v250, s59, 37
	v_writelane_b32 v250, s60, 38
	v_writelane_b32 v250, s61, 39
	v_writelane_b32 v250, s62, 40
	v_writelane_b32 v250, s63, 41
	s_load_dwordx16 s[48:63], s[0:1], 0x80
	s_cbranch_scc0 .LBB0_16
	s_getpc_b64 s[98:99]
